# EpiScale GEMM epilogue: the eight per-row rstd reductions are computed in one batch right after the partial-sum loads (two LDS round trips instead of sixteen); stores and addressing unchanged
# speedup vs baseline: 1.0028x; 1.0028x over previous
;     DI void operator()(const f32x4 (&acc)[2][2][4][2], const pg8::Unit& u, int wr, int wc, int fr, int fq) const {
;         const int row0 = u.pm * 256 + wr * 64 + fr, col0 = u.pn * 256 + wc * 32 + 8 * fq;
;         f32x4 pp[8];
; #pragma unroll
;         for (int g = 0; g < 8; ++g) pp[g] = *(const f32x4*)(ssq + (size_t)(row0 + (g >> 2) * 128 + (g & 3) * 16) * 16 + 4 * fq);
; #pragma unroll
;         for (int ai = 0; ai < 2; ++ai)
; #pragma unroll
;             for (int m = 0; m < 4; ++m) {
;                 const int row = row0 + ai * 128 + m * 16;
;                 const f32x4 p = pp[ai * 4 + m];
;                 float s = (p[0] + p[1]) + (p[2] + p[3]);
;                 s += __shfl_xor(s, 16); s += __shfl_xor(s, 32);
;                 const float rstd = rsqrtf(s * (1.0f / D) + EPS);
;                 bf16_t* rowp = O + (size_t)row * ldc + col0;
; #pragma unroll
;                 for (int bj = 0; bj < 2; ++bj) {
;                     f32x4 v0 = acc[ai][bj][m][0] * rstd, v1 = acc[ai][bj][m][1] * rstd;
;                     if (act) {
; #pragma unroll
;                         for (int k = 0; k < 4; ++k) { float a = fmaxf(v0[k], 0.f), b = fmaxf(v1[k], 0.f); v0[k] = a * a; v1[k] = b * b; }
.LBB0_470:
	v_lshl_add_u32 v190, s38, 8, v214
	v_ashrrev_i32_e32 v191, 31, v190
	v_lshlrev_b64 v[56:57], 6, v[190:191]
	v_lshl_add_u64 v[56:57], v[170:171], 0, v[56:57]
	global_load_dwordx4 v[192:195], v[56:57], off
	v_or_b32_e32 v188, 16, v190
	v_ashrrev_i32_e32 v189, 31, v188
	v_lshlrev_b64 v[56:57], 6, v[188:189]
	v_or_b32_e32 v186, 32, v190
	v_lshl_add_u64 v[56:57], v[170:171], 0, v[56:57]
	v_ashrrev_i32_e32 v187, 31, v186
	global_load_dwordx4 v[152:155], v[56:57], off
	v_lshlrev_b64 v[56:57], 6, v[186:187]
	v_or_b32_e32 v184, 48, v190
	v_lshl_add_u64 v[56:57], v[170:171], 0, v[56:57]
	v_ashrrev_i32_e32 v185, 31, v184
	global_load_dwordx4 v[148:151], v[56:57], off
	v_lshlrev_b64 v[56:57], 6, v[184:185]
	v_add_u32_e32 v182, 0x80, v190
	v_lshl_add_u64 v[56:57], v[170:171], 0, v[56:57]
	v_ashrrev_i32_e32 v183, 31, v182
	global_load_dwordx4 v[136:139], v[56:57], off
	v_lshlrev_b64 v[56:57], 6, v[182:183]
	v_add_u32_e32 v180, 0x90, v190
	v_lshl_add_u64 v[56:57], v[170:171], 0, v[56:57]
	v_ashrrev_i32_e32 v181, 31, v180
	global_load_dwordx4 v[116:119], v[56:57], off
	v_lshlrev_b64 v[56:57], 6, v[180:181]
	v_add_u32_e32 v178, 0xa0, v190
	v_lshl_add_u64 v[56:57], v[170:171], 0, v[56:57]
	v_ashrrev_i32_e32 v179, 31, v178
	global_load_dwordx4 v[96:99], v[56:57], off
	v_lshlrev_b64 v[56:57], 6, v[178:179]
	v_add_u32_e32 v176, 0xb0, v190
	v_lshl_add_u64 v[56:57], v[170:171], 0, v[56:57]
	v_ashrrev_i32_e32 v177, 31, v176
	global_load_dwordx4 v[76:79], v[56:57], off
	v_lshlrev_b64 v[56:57], 6, v[176:177]
	v_lshl_add_u64 v[56:57], v[170:171], 0, v[56:57]
	global_load_dwordx4 v[56:59], v[56:57], off
	v_and_b32_e32 v179, 64, v198
	v_xor_b32_e32 v177, 16, v198
	v_add_u32_e32 v179, 64, v179
	v_cmp_lt_i32_e32 vcc, v177, v179
	v_xor_b32_e32 v181, 32, v198
	v_readlane_b32 s48, v250, 18
	v_cndmask_b32_e32 v177, v198, v177, vcc
	v_cmp_lt_i32_e32 vcc, v181, v179
	v_lshlrev_b32_e32 v177, 2, v177
	v_readlane_b32 s49, v250, 19
	v_cndmask_b32_e32 v179, v198, v181, vcc
	v_lshlrev_b32_e32 v179, 2, v179
	v_readlane_b32 s50, v250, 20
	v_readlane_b32 s51, v250, 21
	v_readlane_b32 s52, v250, 22
	v_readlane_b32 s53, v250, 23
	v_readlane_b32 s54, v250, 24
	v_readlane_b32 s55, v250, 25
	v_readlane_b32 s56, v250, 26
	v_readlane_b32 s57, v250, 27
	v_readlane_b32 s58, v250, 28
	v_readlane_b32 s59, v250, 29
	v_readlane_b32 s60, v250, 30
	v_readlane_b32 s61, v250, 31
	v_readlane_b32 s62, v250, 32
	v_readlane_b32 s63, v250, 33
	s_waitcnt vmcnt(0)
	v_add_f32_e32 v220, v193, v192
	v_add_f32_e32 v221, v194, v195
	v_add_f32_e32 v220, v220, v221
	v_add_f32_e32 v222, v153, v152
	v_add_f32_e32 v223, v154, v155
	v_add_f32_e32 v222, v222, v223
	v_add_f32_e32 v224, v149, v148
	v_add_f32_e32 v225, v150, v151
	v_add_f32_e32 v224, v224, v225
	v_add_f32_e32 v226, v137, v136
	v_add_f32_e32 v227, v138, v139
	v_add_f32_e32 v226, v226, v227
	v_add_f32_e32 v228, v117, v116
	v_add_f32_e32 v229, v118, v119
	v_add_f32_e32 v228, v228, v229
	v_add_f32_e32 v230, v97, v96
	v_add_f32_e32 v231, v98, v99
	v_add_f32_e32 v230, v230, v231
	v_add_f32_e32 v232, v77, v76
	v_add_f32_e32 v233, v78, v79
	v_add_f32_e32 v232, v232, v233
	v_add_f32_e32 v234, v57, v56
	v_add_f32_e32 v235, v58, v59
	v_add_f32_e32 v234, v234, v235
	ds_bpermute_b32 v221, v177, v220
	ds_bpermute_b32 v223, v177, v222
	ds_bpermute_b32 v225, v177, v224
	ds_bpermute_b32 v227, v177, v226
	ds_bpermute_b32 v229, v177, v228
	ds_bpermute_b32 v231, v177, v230
	ds_bpermute_b32 v233, v177, v232
	ds_bpermute_b32 v235, v177, v234
	s_waitcnt lgkmcnt(0)
	v_add_f32_e32 v220, v220, v221
	v_add_f32_e32 v222, v222, v223
	v_add_f32_e32 v224, v224, v225
	v_add_f32_e32 v226, v226, v227
	v_add_f32_e32 v228, v228, v229
	v_add_f32_e32 v230, v230, v231
	v_add_f32_e32 v232, v232, v233
	v_add_f32_e32 v234, v234, v235
	ds_bpermute_b32 v221, v179, v220
	ds_bpermute_b32 v223, v179, v222
	ds_bpermute_b32 v225, v179, v224
	ds_bpermute_b32 v227, v179, v226
	ds_bpermute_b32 v229, v179, v228
	ds_bpermute_b32 v231, v179, v230
	ds_bpermute_b32 v233, v179, v232
	ds_bpermute_b32 v235, v179, v234
	s_waitcnt lgkmcnt(0)
	v_add_f32_e32 v220, v220, v221
	v_add_f32_e32 v222, v222, v223
	v_add_f32_e32 v224, v224, v225
	v_add_f32_e32 v226, v226, v227
	v_add_f32_e32 v228, v228, v229
	v_add_f32_e32 v230, v230, v231
	v_add_f32_e32 v232, v232, v233
	v_add_f32_e32 v234, v234, v235
	v_fmamk_f32 v220, v220, 0x3a800000, v162
	v_fmamk_f32 v222, v222, 0x3a800000, v162
	v_fmamk_f32 v224, v224, 0x3a800000, v162
	v_fmamk_f32 v226, v226, 0x3a800000, v162
	v_fmamk_f32 v228, v228, 0x3a800000, v162
	v_fmamk_f32 v230, v230, 0x3a800000, v162
	v_fmamk_f32 v232, v232, 0x3a800000, v162
	v_fmamk_f32 v234, v234, 0x3a800000, v162
	v_rsq_f32_e32 v220, v220
	v_rsq_f32_e32 v222, v222
	v_rsq_f32_e32 v224, v224
	v_rsq_f32_e32 v226, v226
	v_rsq_f32_e32 v228, v228
	v_rsq_f32_e32 v230, v230
	v_rsq_f32_e32 v232, v232
	v_rsq_f32_e32 v234, v234
	s_nop 0
	v_mov_b32_e32 v192, v220
	v_pk_mul_f32 v[194:195], v[140:141], v[192:193] op_sel_hi:[1,0]
	v_cndmask_b32_e64 v140, 0, 1, s[0:1]
	v_pk_mul_f32 v[146:147], v[146:147], v[192:193] op_sel_hi:[1,0]
	v_pk_mul_f32 v[144:145], v[144:145], v[192:193] op_sel_hi:[1,0]
	v_pk_mul_f32 v[142:143], v[142:143], v[192:193] op_sel_hi:[1,0]
	v_cmp_ne_u32_e64 s[38:39], 1, v140
	s_andn2_b64 vcc, exec, s[0:1]
	s_cbranch_vccnz .LBB0_472
	v_max_f32_e32 v140, v144, v144
	v_max_f32_e32 v144, v195, v195
	v_max_f32_e32 v141, v194, v194
	v_max_f32_e32 v195, 0, v144
	v_max_f32_e32 v144, v146, v146
	v_max_f32_e32 v194, 0, v141
	v_max_f32_e32 v141, v145, v145
	v_max_f32_e32 v146, 0, v144
	v_max_f32_e32 v142, v142, v142
	v_max_f32_e32 v144, v147, v147
	v_max_f32_e32 v143, v143, v143
	v_max_f32_e32 v140, 0, v140
	v_max_f32_e32 v141, 0, v141
	v_max_f32_e32 v142, 0, v142
	v_max_f32_e32 v147, 0, v144
	v_max_f32_e32 v143, 0, v143
	v_pk_mul_f32 v[144:145], v[140:141], v[140:141]
	v_pk_mul_f32 v[146:147], v[146:147], v[146:147]
	v_pk_mul_f32 v[194:195], v[194:195], v[194:195]
	v_pk_mul_f32 v[142:143], v[142:143], v[142:143]

; DI unsigned pk(float lo, float hi) { return pg8::cvt_pk_bf16(lo, hi); }
;     DI void operator()(const f32x4 (&acc)[2][2][4][2], const pg8::Unit& u, int wr, int wc, int fr, int fq) const {
;     ...
;                 const int row = row0 + ai * 128 + m * 16;
;                 const f32x4 p = pp[ai * 4 + m];
;                 float s = (p[0] + p[1]) + (p[2] + p[3]);
;                 s += __shfl_xor(s, 16); s += __shfl_xor(s, 32);
;                 const float rstd = rsqrtf(s * (1.0f / D) + EPS);
;                 bf16_t* rowp = O + (size_t)row * ldc + col0;
; #pragma unroll
;                 for (int bj = 0; bj < 2; ++bj) {
;                     f32x4 v0 = acc[ai][bj][m][0] * rstd, v1 = acc[ai][bj][m][1] * rstd;
;                     if (act) {
; #pragma unroll
;                         for (int k = 0; k < 4; ++k) { float a = fmaxf(v0[k], 0.f), b = fmaxf(v1[k], 0.f); v0[k] = a * a; v1[k] = b * b; }
;                     }
;                     u32x4 w; w.x = pk(v0[0], v0[1]); w.y = pk(v0[2], v0[3]); w.z = pk(v1[0], v1[1]); w.w = pk(v1[2], v1[3]);
;                     *(u32x4*)(rowp + bj * 128) = w;
.LBB0_474:
	v_cvt_pk_bf16_f32 v132, v132, v133
	v_cvt_pk_bf16_f32 v133, v134, v135
	v_cvt_pk_bf16_f32 v134, v128, v129
	v_cvt_pk_bf16_f32 v135, v130, v131
	global_store_dwordx4 v[190:191], v[132:135], off offset:256 nt
	v_mov_b32_e32 v128, v222
	v_pk_mul_f32 v[126:127], v[126:127], v[128:129] op_sel_hi:[1,0]
	v_pk_mul_f32 v[124:125], v[124:125], v[128:129] op_sel_hi:[1,0]
	v_pk_mul_f32 v[122:123], v[122:123], v[128:129] op_sel_hi:[1,0]
	v_pk_mul_f32 v[120:121], v[120:121], v[128:129] op_sel_hi:[1,0]
	s_and_b64 vcc, exec, s[38:39]
	s_cbranch_vccnz .LBB0_476
	v_max_f32_e32 v124, v124, v124
	v_max_f32_e32 v120, v120, v120
	v_max_f32_e32 v125, v125, v125
	v_max_f32_e32 v121, v121, v121
	v_max_f32_e32 v126, v126, v126
	v_max_f32_e32 v122, v122, v122
	v_max_f32_e32 v127, v127, v127
	v_max_f32_e32 v123, v123, v123
	v_max_f32_e32 v124, 0, v124
	v_max_f32_e32 v120, 0, v120
	v_max_f32_e32 v125, 0, v125
	v_max_f32_e32 v121, 0, v121
	v_max_f32_e32 v126, 0, v126
	v_max_f32_e32 v122, 0, v122
	v_max_f32_e32 v127, 0, v127
	v_max_f32_e32 v123, 0, v123
	v_pk_mul_f32 v[124:125], v[124:125], v[124:125]
	v_pk_mul_f32 v[126:127], v[126:127], v[126:127]
	v_pk_mul_f32 v[120:121], v[120:121], v[120:121]
	v_pk_mul_f32 v[122:123], v[122:123], v[122:123]

; DI unsigned pk(float lo, float hi) { return pg8::cvt_pk_bf16(lo, hi); }
;     DI void operator()(const f32x4 (&acc)[2][2][4][2], const pg8::Unit& u, int wr, int wc, int fr, int fq) const {
;     ...
;                 const int row = row0 + ai * 128 + m * 16;
;                 const f32x4 p = pp[ai * 4 + m];
;                 float s = (p[0] + p[1]) + (p[2] + p[3]);
;                 s += __shfl_xor(s, 16); s += __shfl_xor(s, 32);
;                 const float rstd = rsqrtf(s * (1.0f / D) + EPS);
;                 bf16_t* rowp = O + (size_t)row * ldc + col0;
; #pragma unroll
;                 for (int bj = 0; bj < 2; ++bj) {
;                     f32x4 v0 = acc[ai][bj][m][0] * rstd, v1 = acc[ai][bj][m][1] * rstd;
;                     if (act) {
; #pragma unroll
;                         for (int k = 0; k < 4; ++k) { float a = fmaxf(v0[k], 0.f), b = fmaxf(v1[k], 0.f); v0[k] = a * a; v1[k] = b * b; }
;                     }
;                     u32x4 w; w.x = pk(v0[0], v0[1]); w.y = pk(v0[2], v0[3]); w.z = pk(v1[0], v1[1]); w.w = pk(v1[2], v1[3]);
;                     *(u32x4*)(rowp + bj * 128) = w;
.LBB0_478:
	v_cvt_pk_bf16_f32 v112, v112, v113
	v_cvt_pk_bf16_f32 v113, v114, v115
	v_cvt_pk_bf16_f32 v114, v108, v109
	v_cvt_pk_bf16_f32 v115, v110, v111
	global_store_dwordx4 v[130:131], v[112:115], off offset:256 nt
	v_mov_b32_e32 v108, v224
	v_pk_mul_f32 v[106:107], v[106:107], v[108:109] op_sel_hi:[1,0]
	v_pk_mul_f32 v[104:105], v[104:105], v[108:109] op_sel_hi:[1,0]
	v_pk_mul_f32 v[102:103], v[102:103], v[108:109] op_sel_hi:[1,0]
	v_pk_mul_f32 v[100:101], v[100:101], v[108:109] op_sel_hi:[1,0]
	s_and_b64 vcc, exec, s[38:39]
	s_cbranch_vccnz .LBB0_480
	v_max_f32_e32 v104, v104, v104
	v_max_f32_e32 v100, v100, v100
	v_max_f32_e32 v105, v105, v105
	v_max_f32_e32 v101, v101, v101
	v_max_f32_e32 v106, v106, v106
	v_max_f32_e32 v102, v102, v102
	v_max_f32_e32 v107, v107, v107
	v_max_f32_e32 v103, v103, v103
	v_max_f32_e32 v104, 0, v104
	v_max_f32_e32 v100, 0, v100
	v_max_f32_e32 v105, 0, v105
	v_max_f32_e32 v101, 0, v101
	v_max_f32_e32 v106, 0, v106
	v_max_f32_e32 v102, 0, v102
	v_max_f32_e32 v107, 0, v107
	v_max_f32_e32 v103, 0, v103
	v_pk_mul_f32 v[104:105], v[104:105], v[104:105]
	v_pk_mul_f32 v[106:107], v[106:107], v[106:107]
	v_pk_mul_f32 v[100:101], v[100:101], v[100:101]
	v_pk_mul_f32 v[102:103], v[102:103], v[102:103]

; DI unsigned pk(float lo, float hi) { return pg8::cvt_pk_bf16(lo, hi); }
;     DI void operator()(const f32x4 (&acc)[2][2][4][2], const pg8::Unit& u, int wr, int wc, int fr, int fq) const {
;     ...
;                 const int row = row0 + ai * 128 + m * 16;
;                 const f32x4 p = pp[ai * 4 + m];
;                 float s = (p[0] + p[1]) + (p[2] + p[3]);
;                 s += __shfl_xor(s, 16); s += __shfl_xor(s, 32);
;                 const float rstd = rsqrtf(s * (1.0f / D) + EPS);
;                 bf16_t* rowp = O + (size_t)row * ldc + col0;
; #pragma unroll
;                 for (int bj = 0; bj < 2; ++bj) {
;                     f32x4 v0 = acc[ai][bj][m][0] * rstd, v1 = acc[ai][bj][m][1] * rstd;
;                     if (act) {
; #pragma unroll
;                         for (int k = 0; k < 4; ++k) { float a = fmaxf(v0[k], 0.f), b = fmaxf(v1[k], 0.f); v0[k] = a * a; v1[k] = b * b; }
;                     }
;                     u32x4 w; w.x = pk(v0[0], v0[1]); w.y = pk(v0[2], v0[3]); w.z = pk(v1[0], v1[1]); w.w = pk(v1[2], v1[3]);
;                     *(u32x4*)(rowp + bj * 128) = w;
.LBB0_482:
	v_cvt_pk_bf16_f32 v92, v92, v93
	v_cvt_pk_bf16_f32 v93, v94, v95
	v_cvt_pk_bf16_f32 v94, v88, v89
	v_cvt_pk_bf16_f32 v95, v90, v91
	global_store_dwordx4 v[110:111], v[92:95], off offset:256 nt
	v_mov_b32_e32 v88, v226
	v_pk_mul_f32 v[86:87], v[86:87], v[88:89] op_sel_hi:[1,0]
	v_pk_mul_f32 v[84:85], v[84:85], v[88:89] op_sel_hi:[1,0]
	v_pk_mul_f32 v[82:83], v[82:83], v[88:89] op_sel_hi:[1,0]
	v_pk_mul_f32 v[80:81], v[80:81], v[88:89] op_sel_hi:[1,0]
	s_and_b64 vcc, exec, s[38:39]
	s_cbranch_vccnz .LBB0_484
	v_max_f32_e32 v84, v84, v84
	v_max_f32_e32 v80, v80, v80
	v_max_f32_e32 v85, v85, v85
	v_max_f32_e32 v81, v81, v81
	v_max_f32_e32 v86, v86, v86
	v_max_f32_e32 v82, v82, v82
	v_max_f32_e32 v87, v87, v87
	v_max_f32_e32 v83, v83, v83
	v_max_f32_e32 v84, 0, v84
	v_max_f32_e32 v80, 0, v80
	v_max_f32_e32 v85, 0, v85
	v_max_f32_e32 v81, 0, v81
	v_max_f32_e32 v86, 0, v86
	v_max_f32_e32 v82, 0, v82
	v_max_f32_e32 v87, 0, v87
	v_max_f32_e32 v83, 0, v83
	v_pk_mul_f32 v[84:85], v[84:85], v[84:85]
	v_pk_mul_f32 v[86:87], v[86:87], v[86:87]
	v_pk_mul_f32 v[80:81], v[80:81], v[80:81]
	v_pk_mul_f32 v[82:83], v[82:83], v[82:83]

; DI unsigned pk(float lo, float hi) { return pg8::cvt_pk_bf16(lo, hi); }
;     DI void operator()(const f32x4 (&acc)[2][2][4][2], const pg8::Unit& u, int wr, int wc, int fr, int fq) const {
;     ...
;                 const int row = row0 + ai * 128 + m * 16;
;                 const f32x4 p = pp[ai * 4 + m];
;                 float s = (p[0] + p[1]) + (p[2] + p[3]);
;                 s += __shfl_xor(s, 16); s += __shfl_xor(s, 32);
;                 const float rstd = rsqrtf(s * (1.0f / D) + EPS);
;                 bf16_t* rowp = O + (size_t)row * ldc + col0;
; #pragma unroll
;                 for (int bj = 0; bj < 2; ++bj) {
;                     f32x4 v0 = acc[ai][bj][m][0] * rstd, v1 = acc[ai][bj][m][1] * rstd;
;                     if (act) {
; #pragma unroll
;                         for (int k = 0; k < 4; ++k) { float a = fmaxf(v0[k], 0.f), b = fmaxf(v1[k], 0.f); v0[k] = a * a; v1[k] = b * b; }
;                     }
;                     u32x4 w; w.x = pk(v0[0], v0[1]); w.y = pk(v0[2], v0[3]); w.z = pk(v1[0], v1[1]); w.w = pk(v1[2], v1[3]);
;                     *(u32x4*)(rowp + bj * 128) = w;
.LBB0_486:
	v_cvt_pk_bf16_f32 v72, v72, v73
	v_cvt_pk_bf16_f32 v73, v74, v75
	v_cvt_pk_bf16_f32 v74, v68, v69
	v_cvt_pk_bf16_f32 v75, v70, v71
	global_store_dwordx4 v[90:91], v[72:75], off offset:256 nt
	v_mov_b32_e32 v68, v228
	v_pk_mul_f32 v[66:67], v[66:67], v[68:69] op_sel_hi:[1,0]
	v_pk_mul_f32 v[64:65], v[64:65], v[68:69] op_sel_hi:[1,0]
	v_pk_mul_f32 v[62:63], v[62:63], v[68:69] op_sel_hi:[1,0]
	v_pk_mul_f32 v[60:61], v[60:61], v[68:69] op_sel_hi:[1,0]
	s_and_b64 vcc, exec, s[38:39]
	s_cbranch_vccnz .LBB0_488
	v_max_f32_e32 v64, v64, v64
	v_max_f32_e32 v60, v60, v60
	v_max_f32_e32 v65, v65, v65
	v_max_f32_e32 v61, v61, v61
	v_max_f32_e32 v66, v66, v66
	v_max_f32_e32 v62, v62, v62
	v_max_f32_e32 v67, v67, v67
	v_max_f32_e32 v63, v63, v63
	v_max_f32_e32 v64, 0, v64
	v_max_f32_e32 v60, 0, v60
	v_max_f32_e32 v65, 0, v65
	v_max_f32_e32 v61, 0, v61
	v_max_f32_e32 v66, 0, v66
	v_max_f32_e32 v62, 0, v62
	v_max_f32_e32 v67, 0, v67
	v_max_f32_e32 v63, 0, v63
	v_pk_mul_f32 v[64:65], v[64:65], v[64:65]
	v_pk_mul_f32 v[66:67], v[66:67], v[66:67]
	v_pk_mul_f32 v[60:61], v[60:61], v[60:61]
	v_pk_mul_f32 v[62:63], v[62:63], v[62:63]

; DI unsigned pk(float lo, float hi) { return pg8::cvt_pk_bf16(lo, hi); }
;     DI void operator()(const f32x4 (&acc)[2][2][4][2], const pg8::Unit& u, int wr, int wc, int fr, int fq) const {
;     ...
;                 const int row = row0 + ai * 128 + m * 16;
;                 const f32x4 p = pp[ai * 4 + m];
;                 float s = (p[0] + p[1]) + (p[2] + p[3]);
;                 s += __shfl_xor(s, 16); s += __shfl_xor(s, 32);
;                 const float rstd = rsqrtf(s * (1.0f / D) + EPS);
;                 bf16_t* rowp = O + (size_t)row * ldc + col0;
; #pragma unroll
;                 for (int bj = 0; bj < 2; ++bj) {
;                     f32x4 v0 = acc[ai][bj][m][0] * rstd, v1 = acc[ai][bj][m][1] * rstd;
;                     if (act) {
; #pragma unroll
;                         for (int k = 0; k < 4; ++k) { float a = fmaxf(v0[k], 0.f), b = fmaxf(v1[k], 0.f); v0[k] = a * a; v1[k] = b * b; }
;                     }
;                     u32x4 w; w.x = pk(v0[0], v0[1]); w.y = pk(v0[2], v0[3]); w.z = pk(v1[0], v1[1]); w.w = pk(v1[2], v1[3]);
;                     *(u32x4*)(rowp + bj * 128) = w;
.LBB0_490:
	v_cvt_pk_bf16_f32 v52, v52, v53
	v_cvt_pk_bf16_f32 v53, v54, v55
	v_cvt_pk_bf16_f32 v54, v48, v49
	v_cvt_pk_bf16_f32 v55, v50, v51
	global_store_dwordx4 v[70:71], v[52:55], off offset:256 nt
	v_mov_b32_e32 v48, v230
	v_pk_mul_f32 v[46:47], v[46:47], v[48:49] op_sel_hi:[1,0]
	v_pk_mul_f32 v[44:45], v[44:45], v[48:49] op_sel_hi:[1,0]
	v_pk_mul_f32 v[42:43], v[42:43], v[48:49] op_sel_hi:[1,0]
	v_pk_mul_f32 v[40:41], v[40:41], v[48:49] op_sel_hi:[1,0]
	s_and_b64 vcc, exec, s[38:39]
	s_cbranch_vccnz .LBB0_492
	v_max_f32_e32 v44, v44, v44
	v_max_f32_e32 v40, v40, v40
	v_max_f32_e32 v45, v45, v45
	v_max_f32_e32 v41, v41, v41
	v_max_f32_e32 v46, v46, v46
	v_max_f32_e32 v42, v42, v42
	v_max_f32_e32 v47, v47, v47
	v_max_f32_e32 v43, v43, v43
	v_max_f32_e32 v44, 0, v44
	v_max_f32_e32 v40, 0, v40
	v_max_f32_e32 v45, 0, v45
	v_max_f32_e32 v41, 0, v41
	v_max_f32_e32 v46, 0, v46
	v_max_f32_e32 v42, 0, v42
	v_max_f32_e32 v47, 0, v47
	v_max_f32_e32 v43, 0, v43
	v_pk_mul_f32 v[44:45], v[44:45], v[44:45]
	v_pk_mul_f32 v[46:47], v[46:47], v[46:47]
	v_pk_mul_f32 v[40:41], v[40:41], v[40:41]
	v_pk_mul_f32 v[42:43], v[42:43], v[42:43]

; DI unsigned pk(float lo, float hi) { return pg8::cvt_pk_bf16(lo, hi); }
;     DI void operator()(const f32x4 (&acc)[2][2][4][2], const pg8::Unit& u, int wr, int wc, int fr, int fq) const {
;     ...
;                 const int row = row0 + ai * 128 + m * 16;
;                 const f32x4 p = pp[ai * 4 + m];
;                 float s = (p[0] + p[1]) + (p[2] + p[3]);
;                 s += __shfl_xor(s, 16); s += __shfl_xor(s, 32);
;                 const float rstd = rsqrtf(s * (1.0f / D) + EPS);
;                 bf16_t* rowp = O + (size_t)row * ldc + col0;
; #pragma unroll
;                 for (int bj = 0; bj < 2; ++bj) {
;                     f32x4 v0 = acc[ai][bj][m][0] * rstd, v1 = acc[ai][bj][m][1] * rstd;
;                     if (act) {
; #pragma unroll
;                         for (int k = 0; k < 4; ++k) { float a = fmaxf(v0[k], 0.f), b = fmaxf(v1[k], 0.f); v0[k] = a * a; v1[k] = b * b; }
;                     }
;                     u32x4 w; w.x = pk(v0[0], v0[1]); w.y = pk(v0[2], v0[3]); w.z = pk(v1[0], v1[1]); w.w = pk(v1[2], v1[3]);
;                     *(u32x4*)(rowp + bj * 128) = w;
.LBB0_494:
	v_cvt_pk_bf16_f32 v36, v36, v37
	v_cvt_pk_bf16_f32 v37, v38, v39
	v_cvt_pk_bf16_f32 v38, v32, v33
	v_cvt_pk_bf16_f32 v39, v34, v35
	global_store_dwordx4 v[50:51], v[36:39], off offset:256 nt
	v_mov_b32_e32 v32, v232
	v_pk_mul_f32 v[30:31], v[30:31], v[32:33] op_sel_hi:[1,0]
	v_pk_mul_f32 v[28:29], v[28:29], v[32:33] op_sel_hi:[1,0]
	v_pk_mul_f32 v[26:27], v[26:27], v[32:33] op_sel_hi:[1,0]
	v_pk_mul_f32 v[24:25], v[24:25], v[32:33] op_sel_hi:[1,0]
	s_and_b64 vcc, exec, s[38:39]
	s_cbranch_vccnz .LBB0_496
	v_max_f32_e32 v28, v28, v28
	v_max_f32_e32 v24, v24, v24
	v_max_f32_e32 v29, v29, v29
	v_max_f32_e32 v25, v25, v25
	v_max_f32_e32 v30, v30, v30
	v_max_f32_e32 v26, v26, v26
	v_max_f32_e32 v31, v31, v31
	v_max_f32_e32 v27, v27, v27
	v_max_f32_e32 v28, 0, v28
	v_max_f32_e32 v24, 0, v24
	v_max_f32_e32 v29, 0, v29
	v_max_f32_e32 v25, 0, v25
	v_max_f32_e32 v30, 0, v30
	v_max_f32_e32 v26, 0, v26
	v_max_f32_e32 v31, 0, v31
	v_max_f32_e32 v27, 0, v27
	v_pk_mul_f32 v[28:29], v[28:29], v[28:29]
	v_pk_mul_f32 v[30:31], v[30:31], v[30:31]
	v_pk_mul_f32 v[24:25], v[24:25], v[24:25]
	v_pk_mul_f32 v[26:27], v[26:27], v[26:27]

; DI unsigned pk(float lo, float hi) { return pg8::cvt_pk_bf16(lo, hi); }
;     DI void operator()(const f32x4 (&acc)[2][2][4][2], const pg8::Unit& u, int wr, int wc, int fr, int fq) const {
;     ...
;                 const int row = row0 + ai * 128 + m * 16;
;                 const f32x4 p = pp[ai * 4 + m];
;                 float s = (p[0] + p[1]) + (p[2] + p[3]);
;                 s += __shfl_xor(s, 16); s += __shfl_xor(s, 32);
;                 const float rstd = rsqrtf(s * (1.0f / D) + EPS);
;                 bf16_t* rowp = O + (size_t)row * ldc + col0;
; #pragma unroll
;                 for (int bj = 0; bj < 2; ++bj) {
;                     f32x4 v0 = acc[ai][bj][m][0] * rstd, v1 = acc[ai][bj][m][1] * rstd;
;                     if (act) {
; #pragma unroll
;                         for (int k = 0; k < 4; ++k) { float a = fmaxf(v0[k], 0.f), b = fmaxf(v1[k], 0.f); v0[k] = a * a; v1[k] = b * b; }
;                     }
;                     u32x4 w; w.x = pk(v0[0], v0[1]); w.y = pk(v0[2], v0[3]); w.z = pk(v1[0], v1[1]); w.w = pk(v1[2], v1[3]);
;                     *(u32x4*)(rowp + bj * 128) = w;
.LBB0_498:
	v_cvt_pk_bf16_f32 v20, v20, v21
	v_cvt_pk_bf16_f32 v21, v22, v23
	v_cvt_pk_bf16_f32 v22, v16, v17
	v_cvt_pk_bf16_f32 v23, v18, v19
	global_store_dwordx4 v[34:35], v[20:23], off offset:256 nt
	v_mov_b32_e32 v16, v234
	v_pk_mul_f32 v[14:15], v[14:15], v[16:17] op_sel_hi:[1,0]
	v_pk_mul_f32 v[12:13], v[12:13], v[16:17] op_sel_hi:[1,0]
	v_pk_mul_f32 v[10:11], v[10:11], v[16:17] op_sel_hi:[1,0]
	v_pk_mul_f32 v[8:9], v[8:9], v[16:17] op_sel_hi:[1,0]
	s_and_b64 vcc, exec, s[38:39]
	s_cbranch_vccnz .LBB0_500
	v_max_f32_e32 v12, v12, v12
	v_max_f32_e32 v8, v8, v8
	v_max_f32_e32 v13, v13, v13
	v_max_f32_e32 v9, v9, v9
	v_max_f32_e32 v14, v14, v14
	v_max_f32_e32 v10, v10, v10
	v_max_f32_e32 v15, v15, v15
	v_max_f32_e32 v11, v11, v11
	v_max_f32_e32 v12, 0, v12
	v_max_f32_e32 v8, 0, v8
	v_max_f32_e32 v13, 0, v13
	v_max_f32_e32 v9, 0, v9
	v_max_f32_e32 v14, 0, v14
	v_max_f32_e32 v10, 0, v10
	v_max_f32_e32 v15, 0, v15
	v_max_f32_e32 v11, 0, v11
	v_pk_mul_f32 v[12:13], v[12:13], v[12:13]
	v_pk_mul_f32 v[14:15], v[14:15], v[14:15]
	v_pk_mul_f32 v[8:9], v[8:9], v[8:9]
	v_pk_mul_f32 v[10:11], v[10:11], v[10:11]
